# P1 pre-norm row loop rebuilt: next row prefetched, all modulation vectors requested at the top of the iteration, norm_g hoisted
# baseline (speedup 1.0000x reference)
.LBB0_87:
	s_or_b64 exec, exec, s[8:9]
	s_cmp_eq_u32 s95, 0
	s_cselect_b64 s[0:1], -1, 0
	v_writelane_b32 v255, s0, 2
	v_ashrrev_i32_e32 v0, 6, v2
	s_nop 0
	v_writelane_b32 v255, s1, 3
	s_mul_i32 s0, s95, 0xc000
	v_writelane_b32 v255, s0, 4
	v_readlane_b32 s0, v254, 3
	s_nop 1
	v_add_u32_e32 v16, s0, v0
	s_movk_i32 s0, 0x4000
	v_cmp_gt_i32_e32 vcc, s0, v16
	s_and_saveexec_b64 s[8:9], vcc
	s_cbranch_execz .LBB0_94
	v_readlane_b32 s0, v255, 2
	s_lshl_b32 s80, s95, 10
	v_readlane_b32 s1, v255, 3
	s_and_b64 s[14:15], s[0:1], exec
	s_mul_i32 s0, s95, 0xc000
	s_waitcnt lgkmcnt(0)
	s_cselect_b32 s5, s11, s5
	s_cselect_b32 s4, s10, s4
	s_add_u32 s0, s6, s0
	s_addc_u32 s1, s7, 0
	s_add_u32 s10, s0, 0x2b40000
	s_addc_u32 s11, s1, 0
	s_lshl_b64 s[14:15], s[80:81], 2
	v_lshlrev_b32_e32 v0, 3, v2
	v_cmp_lt_i32_e32 vcc, v234, v235
	s_add_u32 s14, s12, s14
	v_and_b32_e32 v0, 0x1f8, v0
	v_cndmask_b32_e32 v1, v233, v234, vcc
	s_addc_u32 s15, s13, s15
	v_lshlrev_b32_e32 v144, 2, v0
	v_lshlrev_b32_e32 v38, 2, v1
	v_xor_b32_e32 v1, 32, v233
	v_lshl_add_u64 v[18:19], s[4:5], 0, v[144:145]
	v_cmp_lt_i32_e32 vcc, v1, v235
	v_lshl_add_u64 v[20:21], s[14:15], 0, v[144:145]
	v_lshlrev_b32_e32 v144, 1, v0
	v_cndmask_b32_e32 v1, v233, v1, vcc
	s_add_u32 s12, s6, 0x1ebf0000
	v_or_b32_e32 v2, 0x200, v0
	v_lshl_add_u64 v[4:5], s[6:7], 0, v[144:145]
	s_mov_b64 s[4:5], 0x16bf0000
	v_lshlrev_b32_e32 v24, 2, v0
	v_lshlrev_b32_e32 v39, 2, v1
	s_addc_u32 s13, s7, 0
	v_lshl_add_u64 v[22:23], v[4:5], 0, s[4:5]
	s_mov_b64 s[6:7], 0
	v_mov_b32_e32 v26, v24
	v_mov_b32_e32 v27, v145
	v_lshlrev_b32_e32 v144, 2, v2
	v_readfirstlane_b32 s6, v16
	v_readlane_b32 s7, v254, 4
	global_load_dwordx4 v[124:127], v[20:21], off
	global_load_dwordx4 v[128:131], v[20:21], off offset:16
	global_load_dwordx4 v[132:135], v[20:21], off offset:2048
	global_load_dwordx4 v[136:139], v[20:21], off offset:2064
	s_lshl_b32 s0, s6, 12
	s_mov_b32 s1, 0
	v_lshl_add_u64 v[0:1], v[18:19], 0, s[0:1]
	global_load_dwordx4 v[60:63], v[0:1], off
	global_load_dwordx4 v[64:67], v[0:1], off offset:16
	global_load_dwordx4 v[68:71], v[0:1], off offset:2048
	global_load_dwordx4 v[72:75], v[0:1], off offset:2064
	global_load_dwordx4 v[6:9], v[20:21], off
	global_load_dwordx4 v[10:13], v[20:21], off offset:16
.Lp1_A:
	s_lshr_b32 s0, s6, 12
	s_mul_i32 s0, s0, 0x3000
	s_add_u32 s4, s10, s0
	s_addc_u32 s5, s11, 0
	s_add_u32 s0, s4, 0x1000
	s_addc_u32 s1, s5, 0
	global_load_dwordx4 v[92:95], v26, s[0:1]
	global_load_dwordx4 v[96:99], v26, s[0:1] offset:16
	global_load_dwordx4 v[100:103], v26, s[4:5]
	global_load_dwordx4 v[104:107], v26, s[4:5] offset:16
	global_load_dwordx4 v[108:111], v26, s[0:1] offset:2048
	global_load_dwordx4 v[112:115], v26, s[0:1] offset:2064
	global_load_dwordx4 v[116:119], v26, s[4:5] offset:2048
	global_load_dwordx4 v[120:123], v26, s[4:5] offset:2064
	s_add_i32 s0, s6, s7
	s_min_u32 s0, s0, 0x3fff
	s_lshl_b32 s0, s0, 12
	s_mov_b32 s1, 0
	v_lshl_add_u64 v[0:1], v[18:19], 0, s[0:1]
	global_load_dwordx4 v[76:79], v[0:1], off
	global_load_dwordx4 v[80:83], v[0:1], off offset:16
	global_load_dwordx4 v[84:87], v[0:1], off offset:2048
	global_load_dwordx4 v[88:91], v[0:1], off offset:2064
	s_waitcnt vmcnt(14)
	v_pk_mul_f32 v[2:3], v[60:61], v[60:61]
	v_pk_mul_f32 v[4:5], v[68:69], v[68:69]
	v_pk_fma_f32 v[2:3], v[62:63], v[62:63], v[2:3]
	v_pk_fma_f32 v[4:5], v[70:71], v[70:71], v[4:5]
	v_pk_fma_f32 v[2:3], v[64:65], v[64:65], v[2:3]
	v_pk_fma_f32 v[4:5], v[72:73], v[72:73], v[4:5]
	v_pk_fma_f32 v[2:3], v[66:67], v[66:67], v[2:3]
	v_pk_fma_f32 v[4:5], v[74:75], v[74:75], v[4:5]
	v_pk_add_f32 v[2:3], v[2:3], v[4:5]
	s_nop 0
	v_add_f32_e32 v25, v2, v3
	s_nop 1
	v_add_f32_dpp v25, v25, v25 quad_perm:[1,0,3,2] row_mask:0xf bank_mask:0xf bound_ctrl:1
	s_nop 1
	v_add_f32_dpp v25, v25, v25 quad_perm:[2,3,0,1] row_mask:0xf bank_mask:0xf bound_ctrl:1
	s_nop 1
	v_add_f32_dpp v25, v25, v25 row_half_mirror row_mask:0xf bank_mask:0xf bound_ctrl:1
	s_nop 1
	v_add_f32_dpp v25, v25, v25 row_mirror row_mask:0xf bank_mask:0xf bound_ctrl:1
	s_nop 0
	ds_bpermute_b32 v2, v38, v25
	s_waitcnt lgkmcnt(0)
	v_add_f32_e32 v25, v25, v2
	s_nop 0
	ds_bpermute_b32 v2, v39, v25
	s_waitcnt lgkmcnt(0)
	v_add_f32_e32 v17, v25, v2
	v_mov_b32_e32 v25, 0x358637bd
	v_fmamk_f32 v17, v17, 0x3a800000, v25
	v_mul_f32_e32 v25, 0x4b800000, v17
	v_cmp_gt_f32_e64 s[4:5], s74, v17
	s_nop 1
	v_cndmask_b32_e64 v17, v17, v25, s[4:5]
	v_rsq_f32_e32 v17, v17
	s_nop 0
	v_mul_f32_e32 v25, 0x45800000, v17
	v_cndmask_b32_e64 v36, v17, v25, s[4:5]
	s_nop 0
	v_pk_mul_f32 v[40:41], v[60:61], v[36:37] op_sel_hi:[1,0]
	v_pk_mul_f32 v[42:43], v[62:63], v[36:37] op_sel_hi:[1,0]
	v_pk_mul_f32 v[44:45], v[64:65], v[36:37] op_sel_hi:[1,0]
	v_pk_mul_f32 v[46:47], v[66:67], v[36:37] op_sel_hi:[1,0]
	v_pk_mul_f32 v[48:49], v[68:69], v[36:37] op_sel_hi:[1,0]
	v_pk_mul_f32 v[50:51], v[70:71], v[36:37] op_sel_hi:[1,0]
	v_pk_mul_f32 v[52:53], v[72:73], v[36:37] op_sel_hi:[1,0]
	v_pk_mul_f32 v[54:55], v[74:75], v[36:37] op_sel_hi:[1,0]
	v_pk_mul_f32 v[40:41], v[124:125], v[40:41]
	v_pk_mul_f32 v[42:43], v[126:127], v[42:43]
	v_pk_mul_f32 v[44:45], v[128:129], v[44:45]
	v_pk_mul_f32 v[46:47], v[130:131], v[46:47]
	v_pk_mul_f32 v[48:49], v[132:133], v[48:49]
	v_pk_mul_f32 v[50:51], v[134:135], v[50:51]
	v_pk_mul_f32 v[52:53], v[136:137], v[52:53]
	v_pk_mul_f32 v[54:55], v[138:139], v[54:55]
	s_waitcnt vmcnt(4)
	v_pk_add_f32 v[92:93], v[92:93], 1.0 op_sel_hi:[1,0]
	v_pk_add_f32 v[94:95], v[94:95], 1.0 op_sel_hi:[1,0]
	v_pk_add_f32 v[96:97], v[96:97], 1.0 op_sel_hi:[1,0]
	v_pk_add_f32 v[98:99], v[98:99], 1.0 op_sel_hi:[1,0]
	v_pk_add_f32 v[108:109], v[108:109], 1.0 op_sel_hi:[1,0]
	v_pk_add_f32 v[110:111], v[110:111], 1.0 op_sel_hi:[1,0]
	v_pk_add_f32 v[112:113], v[112:113], 1.0 op_sel_hi:[1,0]
	v_pk_add_f32 v[114:115], v[114:115], 1.0 op_sel_hi:[1,0]
	v_pk_fma_f32 v[40:41], v[92:93], v[40:41], v[100:101]
	v_pk_fma_f32 v[42:43], v[94:95], v[42:43], v[102:103]
	v_pk_fma_f32 v[44:45], v[96:97], v[44:45], v[104:105]
	v_pk_fma_f32 v[46:47], v[98:99], v[46:47], v[106:107]
	v_pk_fma_f32 v[48:49], v[108:109], v[48:49], v[116:117]
	v_pk_fma_f32 v[50:51], v[110:111], v[50:51], v[118:119]
	v_pk_fma_f32 v[52:53], v[112:113], v[52:53], v[120:121]
	v_pk_fma_f32 v[54:55], v[114:115], v[54:55], v[122:123]
	s_lshl_b32 s0, s6, 11
	s_mov_b32 s1, 0
	v_lshl_add_u64 v[34:35], v[22:23], 0, s[0:1]
	v_cvt_pk_bf16_f32 v56, v40, v41
	v_cvt_pk_bf16_f32 v57, v42, v43
	v_cvt_pk_bf16_f32 v58, v44, v45
	v_cvt_pk_bf16_f32 v59, v46, v47
	global_store_dwordx4 v[34:35], v[56:59], off
	v_cvt_pk_bf16_f32 v140, v48, v49
	v_cvt_pk_bf16_f32 v141, v50, v51
	v_cvt_pk_bf16_f32 v142, v52, v53
	v_cvt_pk_bf16_f32 v143, v54, v55
	global_store_dwordx4 v[34:35], v[140:143], off offset:1024
	s_and_b32 s0, s6, 0xfff
	s_cmp_lg_u32 s0, 0
	s_cbranch_scc1 .Lp1_A_nf
	s_lshr_b32 s0, s6, 12
	s_lshl_b32 s0, s0, 12
	s_add_u32 s0, s12, s0
	s_addc_u32 s1, s13, 0
	global_store_dwordx4 v26, v[40:43], s[0:1]
	global_store_dwordx4 v26, v[44:47], s[0:1] offset:16
	global_store_dwordx4 v26, v[48:51], s[0:1] offset:2048
	global_store_dwordx4 v26, v[52:55], s[0:1] offset:2064
.Lp1_A_nf:
	s_add_i32 s6, s6, s7
	s_cmp_lt_u32 s6, 0x4000
	s_cbranch_scc0 .LBB0_94
.Lp1_B:
	s_lshr_b32 s0, s6, 12
	s_mul_i32 s0, s0, 0x3000
	s_add_u32 s4, s10, s0
	s_addc_u32 s5, s11, 0
	s_add_u32 s0, s4, 0x1000
	s_addc_u32 s1, s5, 0
	global_load_dwordx4 v[92:95], v26, s[0:1]
	global_load_dwordx4 v[96:99], v26, s[0:1] offset:16
	global_load_dwordx4 v[100:103], v26, s[4:5]
	global_load_dwordx4 v[104:107], v26, s[4:5] offset:16
	global_load_dwordx4 v[108:111], v26, s[0:1] offset:2048
	global_load_dwordx4 v[112:115], v26, s[0:1] offset:2064
	global_load_dwordx4 v[116:119], v26, s[4:5] offset:2048
	global_load_dwordx4 v[120:123], v26, s[4:5] offset:2064
	s_add_i32 s0, s6, s7
	s_min_u32 s0, s0, 0x3fff
	s_lshl_b32 s0, s0, 12
	s_mov_b32 s1, 0
	v_lshl_add_u64 v[0:1], v[18:19], 0, s[0:1]
	global_load_dwordx4 v[60:63], v[0:1], off
	global_load_dwordx4 v[64:67], v[0:1], off offset:16
	global_load_dwordx4 v[68:71], v[0:1], off offset:2048
	global_load_dwordx4 v[72:75], v[0:1], off offset:2064
	s_waitcnt vmcnt(14)
	v_pk_mul_f32 v[2:3], v[76:77], v[76:77]
	v_pk_mul_f32 v[4:5], v[84:85], v[84:85]
	v_pk_fma_f32 v[2:3], v[78:79], v[78:79], v[2:3]
	v_pk_fma_f32 v[4:5], v[86:87], v[86:87], v[4:5]
	v_pk_fma_f32 v[2:3], v[80:81], v[80:81], v[2:3]
	v_pk_fma_f32 v[4:5], v[88:89], v[88:89], v[4:5]
	v_pk_fma_f32 v[2:3], v[82:83], v[82:83], v[2:3]
	v_pk_fma_f32 v[4:5], v[90:91], v[90:91], v[4:5]
	v_pk_add_f32 v[2:3], v[2:3], v[4:5]
	s_nop 0
	v_add_f32_e32 v25, v2, v3
	s_nop 1
	v_add_f32_dpp v25, v25, v25 quad_perm:[1,0,3,2] row_mask:0xf bank_mask:0xf bound_ctrl:1
	s_nop 1
	v_add_f32_dpp v25, v25, v25 quad_perm:[2,3,0,1] row_mask:0xf bank_mask:0xf bound_ctrl:1
	s_nop 1
	v_add_f32_dpp v25, v25, v25 row_half_mirror row_mask:0xf bank_mask:0xf bound_ctrl:1
	s_nop 1
	v_add_f32_dpp v25, v25, v25 row_mirror row_mask:0xf bank_mask:0xf bound_ctrl:1
	s_nop 0
	ds_bpermute_b32 v2, v38, v25
	s_waitcnt lgkmcnt(0)
	v_add_f32_e32 v25, v25, v2
	s_nop 0
	ds_bpermute_b32 v2, v39, v25
	s_waitcnt lgkmcnt(0)
	v_add_f32_e32 v17, v25, v2
	v_mov_b32_e32 v25, 0x358637bd
	v_fmamk_f32 v17, v17, 0x3a800000, v25
	v_mul_f32_e32 v25, 0x4b800000, v17
	v_cmp_gt_f32_e64 s[4:5], s74, v17
	s_nop 1
	v_cndmask_b32_e64 v17, v17, v25, s[4:5]
	v_rsq_f32_e32 v17, v17
	s_nop 0
	v_mul_f32_e32 v25, 0x45800000, v17
	v_cndmask_b32_e64 v36, v17, v25, s[4:5]
	s_nop 0
	v_pk_mul_f32 v[40:41], v[76:77], v[36:37] op_sel_hi:[1,0]
	v_pk_mul_f32 v[42:43], v[78:79], v[36:37] op_sel_hi:[1,0]
	v_pk_mul_f32 v[44:45], v[80:81], v[36:37] op_sel_hi:[1,0]
	v_pk_mul_f32 v[46:47], v[82:83], v[36:37] op_sel_hi:[1,0]
	v_pk_mul_f32 v[48:49], v[84:85], v[36:37] op_sel_hi:[1,0]
	v_pk_mul_f32 v[50:51], v[86:87], v[36:37] op_sel_hi:[1,0]
	v_pk_mul_f32 v[52:53], v[88:89], v[36:37] op_sel_hi:[1,0]
	v_pk_mul_f32 v[54:55], v[90:91], v[36:37] op_sel_hi:[1,0]
	v_pk_mul_f32 v[40:41], v[124:125], v[40:41]
	v_pk_mul_f32 v[42:43], v[126:127], v[42:43]
	v_pk_mul_f32 v[44:45], v[128:129], v[44:45]
	v_pk_mul_f32 v[46:47], v[130:131], v[46:47]
	v_pk_mul_f32 v[48:49], v[132:133], v[48:49]
	v_pk_mul_f32 v[50:51], v[134:135], v[50:51]
	v_pk_mul_f32 v[52:53], v[136:137], v[52:53]
	v_pk_mul_f32 v[54:55], v[138:139], v[54:55]
	s_waitcnt vmcnt(4)
	v_pk_add_f32 v[92:93], v[92:93], 1.0 op_sel_hi:[1,0]
	v_pk_add_f32 v[94:95], v[94:95], 1.0 op_sel_hi:[1,0]
	v_pk_add_f32 v[96:97], v[96:97], 1.0 op_sel_hi:[1,0]
	v_pk_add_f32 v[98:99], v[98:99], 1.0 op_sel_hi:[1,0]
	v_pk_add_f32 v[108:109], v[108:109], 1.0 op_sel_hi:[1,0]
	v_pk_add_f32 v[110:111], v[110:111], 1.0 op_sel_hi:[1,0]
	v_pk_add_f32 v[112:113], v[112:113], 1.0 op_sel_hi:[1,0]
	v_pk_add_f32 v[114:115], v[114:115], 1.0 op_sel_hi:[1,0]
	v_pk_fma_f32 v[40:41], v[92:93], v[40:41], v[100:101]
	v_pk_fma_f32 v[42:43], v[94:95], v[42:43], v[102:103]
	v_pk_fma_f32 v[44:45], v[96:97], v[44:45], v[104:105]
	v_pk_fma_f32 v[46:47], v[98:99], v[46:47], v[106:107]
	v_pk_fma_f32 v[48:49], v[108:109], v[48:49], v[116:117]
	v_pk_fma_f32 v[50:51], v[110:111], v[50:51], v[118:119]
	v_pk_fma_f32 v[52:53], v[112:113], v[52:53], v[120:121]
	v_pk_fma_f32 v[54:55], v[114:115], v[54:55], v[122:123]
	s_lshl_b32 s0, s6, 11
	s_mov_b32 s1, 0
	v_lshl_add_u64 v[34:35], v[22:23], 0, s[0:1]
	v_cvt_pk_bf16_f32 v56, v40, v41
	v_cvt_pk_bf16_f32 v57, v42, v43
	v_cvt_pk_bf16_f32 v58, v44, v45
	v_cvt_pk_bf16_f32 v59, v46, v47
	global_store_dwordx4 v[34:35], v[56:59], off
	v_cvt_pk_bf16_f32 v140, v48, v49
	v_cvt_pk_bf16_f32 v141, v50, v51
	v_cvt_pk_bf16_f32 v142, v52, v53
	v_cvt_pk_bf16_f32 v143, v54, v55
	global_store_dwordx4 v[34:35], v[140:143], off offset:1024
	s_and_b32 s0, s6, 0xfff
	s_cmp_lg_u32 s0, 0
	s_cbranch_scc1 .Lp1_B_nf
	s_lshr_b32 s0, s6, 12
	s_lshl_b32 s0, s0, 12
	s_add_u32 s0, s12, s0
	s_addc_u32 s1, s13, 0
	global_store_dwordx4 v26, v[40:43], s[0:1]
	global_store_dwordx4 v26, v[44:47], s[0:1] offset:16
	global_store_dwordx4 v26, v[48:51], s[0:1] offset:2048
	global_store_dwordx4 v26, v[52:55], s[0:1] offset:2064
.Lp1_B_nf:
	s_add_i32 s6, s6, s7
	s_cmp_lt_u32 s6, 0x4000
	s_cbranch_scc0 .LBB0_94
	s_branch .Lp1_A
